# NSA selected branch: next K/V tile loads via SGPR base + 32-bit offset instead of 64-bit VGPR addresses
# speedup vs baseline: 1.0088x; 1.0088x over previous
; DI void nsa_item(const Params& p, int bk, int qb, char* smem, float Mb) {
;     ...
;         auto gload = [&](int j) {
; #pragma unroll
;             for (int i = 0; i < 4; ++i) {
;                 const bf16_t* src = ((i >> 1) ? VS : KS) + (size_t)j * 4096 + (l_row + 32 * (i & 1)) * 64 + l_cc * 8;
;                 rg[i] = *(const u32x4*)src;
;             }
;         };
;         auto lstore = [&](int bsel) {
; #pragma unroll
;             for (int i = 0; i < 4; ++i) *(u32x4*)(tb + bsel * 18432 + (i >> 1) * 9216 + (l_row + 32 * (i & 1)) * 144 + l_cc * 16) = rg[i];
;         };
;         unsigned long long m = 0ull, mn = 0ull;
;         int j = next_valid(0, m);
;         gload(j); lstore(0);
;         __syncthreads();
;         int bsel = 0;
;         while (j <= cur) {
;             const int jn = next_valid(j + 1, mn);
;             gload(jn <= cur ? jn : j);
;             const unsigned sub = (unsigned)(m >> (wave * 16)) & 0xffffu;
;             if (sub) {
;                 const char* kb_ = tb + bsel * 18432 + fr * 144 + fq * 16;
;                 bf16x8 kf[4][2], vf[4][2];
; #pragma unroll
;                 for (int k4 = 0; k4 < 4; ++k4) {
;                     kf[k4][0] = *(const bf16x8*)(kb_ + k4 * 16 * 144); kf[k4][1] = *(const bf16x8*)(kb_ + k4 * 16 * 144 + 64);
;                     vf[k4][0] = *(const bf16x8*)(kb_ + 9216 + k4 * 16 * 144); vf[k4][1] = *(const bf16x8*)(kb_ + 9216 + k4 * 16 * 144 + 64);
;                 }
;                 const bool mine = (sub >> fr) & 1u;
;                 const float Ml = mine ? Mb : 3.0e38f;
;                 const bool diag = (j == cur);
; #pragma unroll
;                 for (int g = 0; g < 3; ++g) {
;                     f32x4 st[4];
;                     st_from(kf, qf[g], st, -Ml);
.LBB0_546:
	s_or_b64 exec, exec, s[8:9]
	v_cmp_gt_i32_e64 s[4:5], v242, v238
	v_mov_b32_e32 v207, v189
	v_mov_b32_e32 v205, v189
	v_cndmask_b32_e64 v72, v242, v245, s[4:5]
	v_lshlrev_b32_e32 v72, 13, v72
	v_add3_u32 v254, v72, v188, v204
	v_add3_u32 v255, v72, v206, v204
	global_load_dwordx4 v[72:75], v254, s[50:51]
	global_load_dwordx4 v[76:79], v255, s[50:51]
	global_load_dwordx4 v[80:83], v254, s[36:37]
	global_load_dwordx4 v[84:87], v255, s[36:37]
	v_lshrrev_b64 v[88:89], s93, v[88:89]
	v_cmp_ne_u32_sdwa s[6:7], v88, v189 src0_sel:WORD_0 src1_sel:DWORD
	s_and_saveexec_b64 s[12:13], s[6:7]
	s_cbranch_execz .LBB0_534
	s_mul_i32 s6, s22, 0x4800
	v_add_u32_e32 v116, s6, v239
	ds_read_b128 v[120:123], v116
	ds_read_b128 v[128:131], v116 offset:64
	ds_read_b128 v[132:135], v116 offset:2304
	ds_read_b128 v[136:139], v116 offset:2368
	ds_read_b128 v[144:147], v116 offset:4608
	v_and_b32_e32 v88, v240, v88
	v_cmp_ne_u32_e64 s[6:7], 0, v88
	ds_read_b128 v[148:151], v116 offset:4672
	ds_read_b128 v[152:155], v116 offset:6912
	v_cndmask_b32_e64 v124, v229, v235, s[6:7]
	v_mov_b32_e32 v125, v124
	v_mov_b32_e32 v126, v124
	v_mov_b32_e32 v127, v124
	v_cmp_ne_u32_e64 s[6:7], v245, v238
	s_nop 3
	s_and_b64 s[8:9], exec, s[6:7]
	s_cbranch_scc1 .Lsel_fast
	s_waitcnt lgkmcnt(4)
	v_mfma_f32_16x16x32_bf16 v[92:95], v[132:135], v[0:3], v[124:127]
	v_mfma_f32_16x16x32_bf16 v[88:91], v[120:123], v[0:3], v[124:127]
	s_waitcnt lgkmcnt(3)
	v_mfma_f32_16x16x32_bf16 v[176:179], v[136:139], v[4:7], v[92:95]
	s_waitcnt lgkmcnt(2)
	v_mfma_f32_16x16x32_bf16 v[92:95], v[144:147], v[0:3], v[124:127]
	v_mfma_f32_16x16x32_bf16 v[184:187], v[128:131], v[4:7], v[88:91]
	ds_read_b128 v[108:111], v116 offset:9216
	s_nop 1
	ds_read_b128 v[88:91], v116 offset:9280
	ds_read_b128 v[140:143], v116 offset:6976
	s_waitcnt lgkmcnt(3)
	v_mfma_f32_16x16x32_bf16 v[156:159], v[152:155], v[0:3], v[124:127]
	v_mfma_f32_16x16x32_bf16 v[168:171], v[148:151], v[4:7], v[92:95]
	s_nop 2
	ds_read_b128 v[92:95], v116 offset:11520
	ds_read_b128 v[96:99], v116 offset:11584
	ds_read_b128 v[100:103], v116 offset:13824
	ds_read_b128 v[104:107], v116 offset:13888
	ds_read_b128 v[112:115], v116 offset:16128
	ds_read_b128 v[116:119], v116 offset:16192
	s_waitcnt lgkmcnt(6)
	v_mfma_f32_16x16x32_bf16 v[160:163], v[140:143], v[4:7], v[156:159]
	s_and_saveexec_b64 s[8:9], s[6:7]
	s_xor_b64 s[8:9], exec, s[8:9]
	s_cbranch_execz .LBB0_549
	v_exp_f32_e32 v156, v184
	v_exp_f32_e32 v157, v185
	v_exp_f32_e32 v158, v186
	v_exp_f32_e32 v159, v187
	v_exp_f32_e32 v164, v176
	v_exp_f32_e32 v165, v177
	v_exp_f32_e32 v166, v178
	v_exp_f32_e32 v167, v179
	v_exp_f32_e32 v172, v168
	v_exp_f32_e32 v173, v169
	v_exp_f32_e32 v174, v170
	v_exp_f32_e32 v175, v171
	v_exp_f32_e32 v180, v160
	v_exp_f32_e32 v181, v161
	v_exp_f32_e32 v182, v162
	v_exp_f32_e32 v183, v163
	v_pk_add_f32 v[184:185], v[156:157], v[158:159]
	v_pk_add_f32 v[186:187], v[164:165], v[166:167]
	v_pk_add_f32 v[176:177], v[172:173], v[174:175]
	v_pk_add_f32 v[178:179], v[180:181], v[182:183]
	v_pk_add_f32 v[184:185], v[184:185], v[186:187]
	v_pk_add_f32 v[176:177], v[176:177], v[178:179]
	v_pk_add_f32 v[184:185], v[184:185], v[176:177]
	v_add_f32_e32 v244, v244, v184
	v_add_f32_e32 v244, v244, v185
